# prologue: waves 4-7 run x->bf16 before W_eff so the latency-bound W_eff overlaps the bandwidth-bound conversion
# speedup vs baseline: 1.0114x; 1.0114x over previous
; DEVI const float* IN(int i) { return *(const float* const __attribute__((address_space(4)))*)(kargs() + 8 * i); }
; DEVI void prologue(int wv, LAS unsigned char* lds) {
;     ...
;         const float* wpool = IN(14); const float* pscale = IN(15); const float* wpo = IN(16);
;         for (size_t it = gt; it < (size_t)2 * 65536; it += NGT) {
;             const int l = (int)(it >> 16), r = (int)(it & 65535), kc = r >> 10, n = r & 1023, g = kc >> 4, c0 = (kc & 15) * 8;
;             const float* wp = wpool + (size_t)l * 4 * 128 * 128 + ((size_t)g * 128 + c0) * 128;
;             const float* ps = pscale + l * 512 + g * 128;
;             const float* wo = wpo + (size_t)l * 512 * 1024 + (size_t)g * 128 * 1024 + n;
;             float a0 = 0.f, a1 = 0.f, a2 = 0.f, a3 = 0.f, a4 = 0.f, a5 = 0.f, a6 = 0.f, a7 = 0.f;
.LBB0_331:
	s_or_b64 exec, exec, s[8:9]
	s_mov_b32 s53, 0
	s_bitcmp1_b32 s33, 2
	s_cbranch_scc1 .Lpro_c
.Lpro_b:
	s_mov_b64 s[8:9], 0x20000
	s_mov_b64 s[2:3], s[0:1]
	s_mov_b64 s[24:25], s[0:1]
	s_mov_b64 s[26:27], s[0:1]
	v_cmp_gt_u64_e32 vcc, s[8:9], v[68:69]
	s_and_saveexec_b64 s[8:9], vcc
	s_cbranch_execz .LBB0_336
	s_load_dwordx2 s[28:29], s[0:1], 0x80
	s_load_dwordx2 s[10:11], s[0:1], 0x70
	s_load_dwordx2 s[12:13], s[0:1], 0x78
	v_and_b32_e32 v58, 63, v64
	v_lshrrev_b32_e32 v0, 6, v64
	v_mov_b32_e32 v1, 0
	v_readfirstlane_b32 s15, v68
	v_readfirstlane_b32 s5, v0
	v_lshlrev_b32_e32 v61, 3, v58
	s_mulk_i32 s5, 0x2100
	v_add_u32_e32 v59, s5, v61
	v_mov_b32_e32 v60, s5
	s_waitcnt lgkmcnt(0)

; DEVI unsigned cvtpk(float lo, float hi) { f32x2_t v = {lo, hi}; bf16x2_t b = __builtin_convertvector(v, bf16x2_t); return __builtin_bit_cast(unsigned, b); }
; DEVI float ss4(const f32x4 a) { return (a[0] * a[0] + a[1] * a[1]) + (a[2] * a[2] + a[3] * a[3]); }
; DEVI const float* IN(int i) { return *(const float* const __attribute__((address_space(4)))*)(kargs() + 8 * i); }
; DEVI void prologue(int wv, LAS unsigned char* lds) {
;     ...
;     {
;         const float* x_p = IN(0); const float* x_s = IN(1); bf16_t* xb = (bf16_t*)(ws + O_XB); float* ssqA0 = (float*)(ws + O_SSQA0);
;         for (int row0 = gw; row0 < MT; row0 += 4 * NGW) {
;             f32x4 v[4][4];
; #pragma unroll
;             for (int k = 0; k < 4; ++k) { const int row = row0 + k * NGW;
;                 if (row < MT) { const float* xr = row < MP ? x_p + (size_t)row * 1024 : x_s + (size_t)(row - MP) * 1024;
; #pragma unroll
;                     for (int j = 0; j < 4; ++j) v[k][j] = *(const f32x4*)(xr + 256 * j + 4 * lane); } }
; #pragma unroll
;             for (int k = 0; k < 4; ++k) { const int row = row0 + k * NGW;
;                 if (row < MT) { float s = 0.f;
; #pragma unroll
;                     for (int j = 0; j < 4; ++j) { s += ss4(v[k][j]); u32x2 o; o.x = cvtpk(v[k][j][0], v[k][j][1]); o.y = cvtpk(v[k][j][2], v[k][j][3]); *(u32x2*)(xb + (size_t)row * 1024 + 256 * j + 4 * lane) = o; }
; #pragma unroll
;                     for (int o = 1; o < 64; o <<= 1) s += __shfl_xor(s, o);
;                     if (lane == 0) ssqA0[row] = s; } }
.LBB0_336:
	s_or_b64 exec, exec, s[8:9]
	s_cmp_lg_u32 s53, 0
	s_cbranch_scc1 .Lpro_d
.Lpro_c:
	s_mov_b64 s[2:3], s[0:1]
	s_mov_b64 s[12:13], s[0:1]
	s_cmp_gt_i32 s4, 0x81ff
	v_mbcnt_lo_u32_b32 v232, -1, 0
	s_cbranch_scc1 .LBB0_359
	v_mov_b32_e32 v67, 0
	s_load_dwordx2 s[8:9], s[2:3], 0x0
	s_load_dwordx2 s[10:11], s[12:13], 0x8
	s_waitcnt lgkmcnt(0)
	v_lshl_add_u64 v[2:3], s[20:21], 0, v[66:67]
	s_mov_b64 s[2:3], 0xbbb0800
	v_mbcnt_hi_u32_b32 v1, -1, v232
	v_lshl_add_u64 v[70:71], v[2:3], 0, s[2:3]
	v_and_b32_e32 v2, 64, v1
	v_add_u32_e32 v2, 64, v2
	v_xor_b32_e32 v3, 1, v1
	v_cmp_lt_i32_e32 vcc, v3, v2
	s_add_u32 s15, s20, 0x84800
	v_lshlrev_b32_e32 v0, 2, v34
	v_cndmask_b32_e32 v3, v1, v3, vcc
	v_lshlrev_b32_e32 v66, 2, v3
	v_xor_b32_e32 v3, 2, v1
	v_cmp_lt_i32_e32 vcc, v3, v2
	s_addc_u32 s38, s21, 0
	v_cmp_eq_u32_e64 s[2:3], 0, v34
	v_cndmask_b32_e32 v3, v1, v3, vcc
	v_lshlrev_b32_e32 v72, 2, v3
	v_xor_b32_e32 v3, 4, v1
	v_cmp_lt_i32_e32 vcc, v3, v2
	s_lshl_b32 s39, s16, 4
	s_mul_i32 s40, s16, 24
	v_cndmask_b32_e32 v3, v1, v3, vcc
	v_lshlrev_b32_e32 v73, 2, v3
	v_xor_b32_e32 v3, 8, v1
	v_cmp_lt_i32_e32 vcc, v3, v2
	v_lshlrev_b32_e32 v77, 2, v0
	s_nop 0
	v_cndmask_b32_e32 v3, v1, v3, vcc
	v_lshlrev_b32_e32 v74, 2, v3
	v_xor_b32_e32 v3, 16, v1
	v_cmp_lt_i32_e32 vcc, v3, v2
	s_nop 1
	v_cndmask_b32_e32 v3, v1, v3, vcc
	v_lshlrev_b32_e32 v75, 2, v3
	v_xor_b32_e32 v3, 32, v1
	v_cmp_lt_i32_e32 vcc, v3, v2
	s_nop 1
	v_cndmask_b32_e32 v1, v1, v3, vcc
	v_lshlrev_b32_e32 v76, 2, v1
	s_branch .LBB0_340

; DEVI const float* IN(int i) { return *(const float* const __attribute__((address_space(4)))*)(kargs() + 8 * i); }
; DEVI void prologue(int wv, LAS unsigned char* lds) {
;     ...
;     {
;         const float* x_p = IN(0); const float* x_s = IN(1); bf16_t* xb = (bf16_t*)(ws + O_XB); float* ssqA0 = (float*)(ws + O_SSQA0);
;         for (int row0 = gw; row0 < MT; row0 += 4 * NGW) {
.LBB0_359:
	s_bitcmp1_b32 s33, 2
	s_cbranch_scc0 .Lpro_d
	s_cmp_lg_u32 s53, 0
	s_cbranch_scc1 .Lpro_d
	s_mov_b32 s53, 1
	s_branch .Lpro_b
